# forgetting attention QK: K fragment LDS reads prefetched one pair ahead with alternate buffers, on top of dilated PV prefetch and FFN-up epilogue rewrite
# baseline (speedup 1.0000x reference)
; #define LAS __attribute__((address_space(3)))
; #define MFMA32(a, b, c) __builtin_amdgcn_mfma_f32_32x32x16_bf16((a), (b), (c), 0, 0, 0)
; __device__ __forceinline__ void attn_fox512(LAS unsigned char* lds, const AttnP& P, int b, int h, int qb2) {
;     ...
;         if (actB) {
;             const LAS unsigned char* kb_ = lds + L_K + koff + fro;
;             f32x16 c0, c1;
;             { const LAS float* cb = (const LAS float*)(lds + L_C) + 64 * t + 4 * hi;
; #pragma unroll
;               for (int i = 0; i < 4; ++i) { const f32x4 x0 = *(const LAS f32x4*)(cb + 8 * i), x1 = *(const LAS f32x4*)(cb + 32 + 8 * i);
; #pragma unroll
;                   for (int j = 0; j < 4; ++j) { c0[4 * i + j] = x0[j]; c1[4 * i + j] = x1[j]; } } }
;             f32x16 pA0 = c0, pA1 = c1, pB0 = c0, pB1 = c1;
; #pragma unroll
;             for (int c = 0; c < 4; ++c) { const bf16x8 k0 = *(const LAS bf16x8*)(kb_ + c * 32), k1 = *(const LAS bf16x8*)(kb_ + 32 * ROWB + c * 32);
;                 pB0 = MFMA32(k0, qb[c], pB0); pB1 = MFMA32(k1, qb[c], pB1);
;                 if (actA) { pA0 = MFMA32(k0, qa[c], pA0); pA1 = MFMA32(k1, qa[c], pA1); } }
.LBB0_667:
	v_add_u32_e32 v66, 0x11800, v220
	v_add_u32_e32 v67, 0x11880, v220
	ds_read_b128 v[114:117], v66
	ds_read_b128 v[98:101], v67
	v_add_u32_e32 v66, 0x11820, v220
	v_add_u32_e32 v221, s18, v214
	v_add_u32_e32 v67, 0x118a0, v220
	ds_read_b128 v[118:121], v66
	ds_read_b128 v[102:105], v67
	ds_read_b128 v[178:181], v221
	v_add_u32_e32 v66, 0x11840, v220
	v_add_u32_e32 v68, 0x11860, v220
	v_add_u32_e32 v67, 0x118c0, v220
	ds_read_b128 v[126:129], v68
	ds_read_b128 v[122:125], v66
	ds_read_b128 v[106:109], v67
	v_add_u32_e32 v66, 0x118e0, v220
	ds_read_b128 v[110:113], v66
	ds_read_b128 v[182:185], v221 offset:4608
	ds_read_b128 v[232:235], v221 offset:32
	ds_read_b128 v[236:239], v221 offset:4640
	s_waitcnt lgkmcnt(5)
	v_mfma_f32_32x32x16_bf16 v[66:81], v[178:181], v[150:153], v[114:129]
	s_cmp_le_i32 s4, s39
	s_cselect_b64 s[0:1], -1, 0
	s_cmp_gt_i32 s4, s39
	s_waitcnt lgkmcnt(2)
	v_mfma_f32_32x32x16_bf16 v[82:97], v[182:185], v[150:153], v[98:113]
	s_cbranch_scc1 .LBB0_669
	v_mfma_f32_32x32x16_bf16 v[114:129], v[178:181], v[146:149], v[114:129]
	v_mfma_f32_32x32x16_bf16 v[98:113], v[182:185], v[146:149], v[98:113]
.LBB0_669:
	ds_read_b128 v[182:185], v221 offset:64
	ds_read_b128 v[178:181], v221 offset:4672
	v_cndmask_b32_e64 v194, 0, 1, s[0:1]
	v_cmp_ne_u32_e64 s[40:41], 1, v194
	s_andn2_b64 vcc, exec, s[0:1]
	s_waitcnt lgkmcnt(3)
	v_mfma_f32_32x32x16_bf16 v[66:81], v[232:235], v[158:161], v[66:81]
	s_waitcnt lgkmcnt(2)
	v_mfma_f32_32x32x16_bf16 v[82:97], v[236:239], v[158:161], v[82:97]
	s_cbranch_vccnz .LBB0_671
	v_mfma_f32_32x32x16_bf16 v[114:129], v[232:235], v[154:157], v[114:129]
	v_mfma_f32_32x32x16_bf16 v[98:113], v[236:239], v[154:157], v[98:113]
.LBB0_671:
	ds_read_b128 v[232:235], v221 offset:96
	ds_read_b128 v[236:239], v221 offset:4704
	s_and_b64 vcc, exec, s[40:41]
	s_waitcnt lgkmcnt(3)
	v_mfma_f32_32x32x16_bf16 v[66:81], v[182:185], v[166:169], v[66:81]
	s_waitcnt lgkmcnt(2)
	v_mfma_f32_32x32x16_bf16 v[82:97], v[178:181], v[166:169], v[82:97]
	s_cbranch_vccnz .LBB0_673
	s_nop 0
	v_mfma_f32_32x32x16_bf16 v[114:129], v[182:185], v[162:165], v[114:129]
	v_mfma_f32_32x32x16_bf16 v[98:113], v[178:181], v[162:165], v[98:113]
.LBB0_673:
	s_and_b64 vcc, exec, s[40:41]
	s_mov_b32 s70, 0x41c00000
	s_waitcnt lgkmcnt(1)
	v_mfma_f32_32x32x16_bf16 v[66:81], v[232:235], v[174:177], v[66:81]
	s_waitcnt lgkmcnt(0)
	v_mfma_f32_32x32x16_bf16 v[82:97], v[236:239], v[174:177], v[82:97]
	s_cbranch_vccnz .LBB0_675
	v_mfma_f32_32x32x16_bf16 v[114:129], v[232:235], v[170:173], v[114:129]
	v_mfma_f32_32x32x16_bf16 v[98:113], v[236:239], v[170:173], v[98:113]

; #define LAS __attribute__((address_space(3)))
; #define MFMA32(a, b, c) __builtin_amdgcn_mfma_f32_32x32x16_bf16((a), (b), (c), 0, 0, 0)
; __device__ __forceinline__ void attn_fox512(LAS unsigned char* lds, const AttnP& P, int b, int h, int qb2) {
;     ...
;         if (actB) {
;             const LAS unsigned char* kb_ = lds + L_K + koff + fro;
;             f32x16 c0, c1;
;             { const LAS float* cb = (const LAS float*)(lds + L_C) + 64 * t + 4 * hi;
; #pragma unroll
;               for (int i = 0; i < 4; ++i) { const f32x4 x0 = *(const LAS f32x4*)(cb + 8 * i), x1 = *(const LAS f32x4*)(cb + 32 + 8 * i);
; #pragma unroll
;                   for (int j = 0; j < 4; ++j) { c0[4 * i + j] = x0[j]; c1[4 * i + j] = x1[j]; } } }
;             f32x16 pA0 = c0, pA1 = c1, pB0 = c0, pB1 = c1;
; #pragma unroll
;             for (int c = 0; c < 4; ++c) { const bf16x8 k0 = *(const LAS bf16x8*)(kb_ + c * 32), k1 = *(const LAS bf16x8*)(kb_ + 32 * ROWB + c * 32);
;                 pB0 = MFMA32(k0, qb[c], pB0); pB1 = MFMA32(k1, qb[c], pB1);
;                 if (actA) { pA0 = MFMA32(k0, qa[c], pA0); pA1 = MFMA32(k1, qa[c], pA1); } }
.LBB0_700:
	s_cmp_le_i32 s4, s39
	s_cselect_b64 s[0:1], -1, 0
	s_add_i32 s18, s18, 0
	v_add_u32_e32 v66, 0x11900, v220
	v_add_u32_e32 v67, 0x11980, v220
	ds_read_b128 v[114:117], v66
	ds_read_b128 v[98:101], v67
	v_add_u32_e32 v66, 0x11920, v220
	v_add_u32_e32 v221, s18, v210
	v_add_u32_e32 v67, 0x119a0, v220
	ds_read_b128 v[118:121], v66
	ds_read_b128 v[102:105], v67
	ds_read_b128 v[178:181], v221 offset:9216
	v_add_u32_e32 v66, 0x11940, v220
	v_add_u32_e32 v68, 0x11960, v220
	v_add_u32_e32 v67, 0x119c0, v220
	ds_read_b128 v[126:129], v68
	ds_read_b128 v[122:125], v66
	ds_read_b128 v[106:109], v67
	v_add_u32_e32 v66, 0x119e0, v220
	ds_read_b128 v[110:113], v66
	ds_read_b128 v[182:185], v221 offset:13824
	ds_read_b128 v[232:235], v221 offset:9248
	ds_read_b128 v[236:239], v221 offset:13856
	s_waitcnt lgkmcnt(5)
	v_mfma_f32_32x32x16_bf16 v[66:81], v[178:181], v[150:153], v[114:129]
	s_cmp_gt_i32 s4, s39
	s_waitcnt lgkmcnt(2)
	v_mfma_f32_32x32x16_bf16 v[82:97], v[182:185], v[150:153], v[98:113]
	s_cbranch_scc1 .LBB0_702
	v_mfma_f32_32x32x16_bf16 v[114:129], v[178:181], v[146:149], v[114:129]
	v_mfma_f32_32x32x16_bf16 v[98:113], v[182:185], v[146:149], v[98:113]
.LBB0_702:
	ds_read_b128 v[182:185], v221 offset:9280
	ds_read_b128 v[178:181], v221 offset:13888
	v_cndmask_b32_e64 v194, 0, 1, s[0:1]
	v_cmp_ne_u32_e64 s[40:41], 1, v194
	s_andn2_b64 vcc, exec, s[0:1]
	s_waitcnt lgkmcnt(3)
	v_mfma_f32_32x32x16_bf16 v[66:81], v[232:235], v[158:161], v[66:81]
	s_waitcnt lgkmcnt(2)
	v_mfma_f32_32x32x16_bf16 v[82:97], v[236:239], v[158:161], v[82:97]
	s_cbranch_vccnz .LBB0_704
	v_mfma_f32_32x32x16_bf16 v[114:129], v[232:235], v[154:157], v[114:129]
	v_mfma_f32_32x32x16_bf16 v[98:113], v[236:239], v[154:157], v[98:113]
.LBB0_704:
	ds_read_b128 v[232:235], v221 offset:9312
	ds_read_b128 v[236:239], v221 offset:13920
	s_and_b64 vcc, exec, s[40:41]
	s_waitcnt lgkmcnt(3)
	v_mfma_f32_32x32x16_bf16 v[66:81], v[182:185], v[166:169], v[66:81]
	s_waitcnt lgkmcnt(2)
	v_mfma_f32_32x32x16_bf16 v[82:97], v[178:181], v[166:169], v[82:97]
	s_cbranch_vccnz .LBB0_706
	s_nop 0
	v_mfma_f32_32x32x16_bf16 v[114:129], v[182:185], v[162:165], v[114:129]
	v_mfma_f32_32x32x16_bf16 v[98:113], v[178:181], v[162:165], v[98:113]
.LBB0_706:
	s_and_b64 vcc, exec, s[40:41]
	s_waitcnt lgkmcnt(1)
	v_mfma_f32_32x32x16_bf16 v[66:81], v[232:235], v[174:177], v[66:81]
	s_waitcnt lgkmcnt(0)
	v_mfma_f32_32x32x16_bf16 v[82:97], v[236:239], v[174:177], v[82:97]
	s_cbranch_vccnz .LBB0_708
	s_nop 0
	v_mfma_f32_32x32x16_bf16 v[114:129], v[232:235], v[170:173], v[114:129]
	v_mfma_f32_32x32x16_bf16 v[98:113], v[236:239], v[170:173], v[98:113]
